# v48 plus: grid-barrier spin loops sleep 4 instead of 1 between polls (less poller traffic beside straggler epilogues)
# speedup vs baseline: 1.0035x; 1.0035x over previous
; DI unsigned xb_ld(unsigned* p) { return __hip_atomic_load(p, __ATOMIC_RELAXED, __HIP_MEMORY_SCOPE_AGENT); }
; DI void xcd_barrier_complete(unsigned* bar, unsigned x, unsigned& nloc, unsigned& nx) {
;   const unsigned G = gridDim.x * gridDim.y * gridDim.z;
;   unsigned sum, cnt, mine, sp = 0u;
;   for (;;) {
;     sum = 0u; cnt = 0u; mine = 0u;
; #pragma unroll
;     for (unsigned j = 0; j < 16; ++j) { const unsigned c = xb_ld(&bar[XB_XCNT(j)]); sum += c; cnt += (c > 0u) ? 1u : 0u; mine = (j == x) ? c : mine; }
;     if (sum == G) break;
;     __builtin_amdgcn_s_sleep(1);
;     if ((++sp & 255u) == 0u) { if (xb_ld(&bar[XB_TMO])) break; if (sp > XB_SPIN_CAP) { atomicAdd(&bar[XB_TMO], 1u); break; } }
;   }
;   nloc = mine > 0u ? mine : 1u; nx = cnt > 0u ? cnt : 1u;
.LBB0_237:
	v_readlane_b32 s10, v246, 41
	v_readlane_b32 s11, v246, 42
	s_mov_b64 s[30:31], -1
	s_mov_b64 s[34:35], -1
	s_nop 2
	global_load_dword v0, v189, s[10:11] sc1
	v_readlane_b32 s10, v246, 43
	v_readlane_b32 s11, v246, 44
	s_nop 4
	global_load_dword v1, v189, s[10:11] sc1
	v_readlane_b32 s10, v246, 45
	v_readlane_b32 s11, v246, 46
	s_waitcnt vmcnt(0)
	v_add_u32_e32 v16, v1, v0
	s_nop 2
	global_load_dword v2, v189, s[10:11] sc1
	v_readlane_b32 s10, v246, 47
	v_readlane_b32 s11, v246, 48
	s_waitcnt vmcnt(0)
	v_add_u32_e32 v16, v16, v2
	s_nop 2
	global_load_dword v3, v189, s[10:11] sc1
	v_readlane_b32 s10, v246, 49
	v_readlane_b32 s11, v246, 50
	s_waitcnt vmcnt(0)
	v_add_u32_e32 v16, v16, v3
	s_nop 2
	global_load_dword v4, v189, s[10:11] sc1
	v_readlane_b32 s10, v246, 51
	v_readlane_b32 s11, v246, 52
	s_waitcnt vmcnt(0)
	v_add_u32_e32 v16, v16, v4
	s_nop 2
	global_load_dword v5, v189, s[10:11] sc1
	v_readlane_b32 s10, v246, 53
	v_readlane_b32 s11, v246, 54
	s_waitcnt vmcnt(0)
	v_add_u32_e32 v16, v16, v5
	s_nop 2
	global_load_dword v6, v189, s[10:11] sc1
	v_readlane_b32 s10, v246, 55
	v_readlane_b32 s11, v246, 56
	s_waitcnt vmcnt(0)
	v_add_u32_e32 v16, v16, v6
	s_nop 2
	global_load_dword v7, v189, s[10:11] sc1
	v_readlane_b32 s10, v246, 57
	v_readlane_b32 s11, v246, 58
	s_waitcnt vmcnt(0)
	v_add_u32_e32 v16, v16, v7
	s_nop 2
	global_load_dword v8, v189, s[10:11] sc1
	v_readlane_b32 s10, v246, 59
	v_readlane_b32 s11, v246, 60
	s_waitcnt vmcnt(0)
	v_add_u32_e32 v16, v16, v8
	s_nop 2
	global_load_dword v9, v189, s[10:11] sc1
	v_readlane_b32 s10, v246, 61
	v_readlane_b32 s11, v246, 62
	s_waitcnt vmcnt(0)
	v_add_u32_e32 v16, v16, v9
	s_nop 2
	global_load_dword v10, v189, s[10:11] sc1
	v_readlane_b32 s10, v246, 63
	v_readlane_b32 s11, v245, 0
	s_waitcnt vmcnt(0)
	v_add_u32_e32 v16, v16, v10
	s_nop 2
	global_load_dword v11, v189, s[10:11] sc1
	v_readlane_b32 s10, v245, 1
	v_readlane_b32 s11, v245, 2
	s_waitcnt vmcnt(0)
	v_add_u32_e32 v16, v16, v11
	s_nop 2
	global_load_dword v12, v189, s[10:11] sc1
	v_readlane_b32 s10, v245, 3
	v_readlane_b32 s11, v245, 4
	s_waitcnt vmcnt(0)
	v_add_u32_e32 v16, v16, v12
	s_nop 2
	global_load_dword v13, v189, s[10:11] sc1
	v_readlane_b32 s10, v245, 5
	v_readlane_b32 s11, v245, 6
	s_waitcnt vmcnt(0)
	v_add_u32_e32 v16, v16, v13
	s_nop 2
	global_load_dword v14, v189, s[10:11] sc1
	v_readlane_b32 s10, v245, 7
	v_readlane_b32 s11, v245, 8
	s_waitcnt vmcnt(0)
	v_add_u32_e32 v16, v16, v14
	s_nop 2
	global_load_dword v15, v189, s[10:11] sc1
	s_waitcnt vmcnt(0)
	v_add_u32_e32 v16, v16, v15
	v_cmp_eq_u32_e32 vcc, s7, v16
	s_cbranch_vccnz .LBB0_236
	s_and_b32 s1, s8, 0xff
	s_cmp_eq_u32 s1, 0
	s_mov_b64 s[36:37], -1
	s_sleep 4
	s_cbranch_scc1 .LBB0_241
	s_and_b64 vcc, exec, s[36:37]
	s_cbranch_vccz .LBB0_236

.LBB0_255:
	s_and_b32 s1, s7, 0xff
	s_mov_b64 s[64:65], -1
	s_cmp_lg_u32 s1, 0
	s_mov_b64 s[74:75], -1
	s_sleep 4
	s_cbranch_scc0 .LBB0_258
	s_and_b64 vcc, exec, s[74:75]
	s_cbranch_vccz .LBB0_254

; DI unsigned xb_ld(unsigned* p) { return __hip_atomic_load(p, __ATOMIC_RELAXED, __HIP_MEMORY_SCOPE_AGENT); }
; DI void xcd_barrier_complete(unsigned* bar, unsigned x, unsigned& nloc, unsigned& nx) {
;   const unsigned G = gridDim.x * gridDim.y * gridDim.z;
;   unsigned sum, cnt, mine, sp = 0u;
;   for (;;) {
;     sum = 0u; cnt = 0u; mine = 0u;
; #pragma unroll
;     for (unsigned j = 0; j < 16; ++j) { const unsigned c = xb_ld(&bar[XB_XCNT(j)]); sum += c; cnt += (c > 0u) ? 1u : 0u; mine = (j == x) ? c : mine; }
;     if (sum == G) break;
;     __builtin_amdgcn_s_sleep(1);
;     if ((++sp & 255u) == 0u) { if (xb_ld(&bar[XB_TMO])) break; if (sp > XB_SPIN_CAP) { atomicAdd(&bar[XB_TMO], 1u); break; } }
;   }
;   nloc = mine > 0u ? mine : 1u; nx = cnt > 0u ? cnt : 1u;
.LBB0_374:
	v_readlane_b32 s8, v246, 41
	v_readlane_b32 s9, v246, 42
	s_mov_b64 s[30:31], -1
	s_mov_b64 s[34:35], -1
	s_nop 2
	global_load_dword v0, v189, s[8:9] sc1
	v_readlane_b32 s8, v246, 43
	v_readlane_b32 s9, v246, 44
	s_nop 4
	global_load_dword v1, v189, s[8:9] sc1
	v_readlane_b32 s8, v246, 45
	v_readlane_b32 s9, v246, 46
	s_waitcnt vmcnt(0)
	v_add_u32_e32 v16, v1, v0
	s_nop 2
	global_load_dword v2, v189, s[8:9] sc1
	v_readlane_b32 s8, v246, 47
	v_readlane_b32 s9, v246, 48
	s_waitcnt vmcnt(0)
	v_add_u32_e32 v16, v16, v2
	s_nop 2
	global_load_dword v3, v189, s[8:9] sc1
	v_readlane_b32 s8, v246, 49
	v_readlane_b32 s9, v246, 50
	s_waitcnt vmcnt(0)
	v_add_u32_e32 v16, v16, v3
	s_nop 2
	global_load_dword v4, v189, s[8:9] sc1
	v_readlane_b32 s8, v246, 51
	v_readlane_b32 s9, v246, 52
	s_waitcnt vmcnt(0)
	v_add_u32_e32 v16, v16, v4
	s_nop 2
	global_load_dword v5, v189, s[8:9] sc1
	v_readlane_b32 s8, v246, 53
	v_readlane_b32 s9, v246, 54
	s_waitcnt vmcnt(0)
	v_add_u32_e32 v16, v16, v5
	s_nop 2
	global_load_dword v6, v189, s[8:9] sc1
	v_readlane_b32 s8, v246, 55
	v_readlane_b32 s9, v246, 56
	s_waitcnt vmcnt(0)
	v_add_u32_e32 v16, v16, v6
	s_nop 2
	global_load_dword v7, v189, s[8:9] sc1
	v_readlane_b32 s8, v246, 57
	v_readlane_b32 s9, v246, 58
	s_waitcnt vmcnt(0)
	v_add_u32_e32 v16, v16, v7
	s_nop 2
	global_load_dword v8, v189, s[8:9] sc1
	v_readlane_b32 s8, v246, 59
	v_readlane_b32 s9, v246, 60
	s_waitcnt vmcnt(0)
	v_add_u32_e32 v16, v16, v8
	s_nop 2
	global_load_dword v9, v189, s[8:9] sc1
	v_readlane_b32 s8, v246, 61
	v_readlane_b32 s9, v246, 62
	s_waitcnt vmcnt(0)
	v_add_u32_e32 v16, v16, v9
	s_nop 2
	global_load_dword v10, v189, s[8:9] sc1
	v_readlane_b32 s8, v246, 63
	v_readlane_b32 s9, v245, 0
	s_waitcnt vmcnt(0)
	v_add_u32_e32 v16, v16, v10
	s_nop 2
	global_load_dword v11, v189, s[8:9] sc1
	v_readlane_b32 s8, v245, 1
	v_readlane_b32 s9, v245, 2
	s_waitcnt vmcnt(0)
	v_add_u32_e32 v16, v16, v11
	s_nop 2
	global_load_dword v12, v189, s[8:9] sc1
	v_readlane_b32 s8, v245, 3
	v_readlane_b32 s9, v245, 4
	s_waitcnt vmcnt(0)
	v_add_u32_e32 v16, v16, v12
	s_nop 2
	global_load_dword v13, v189, s[8:9] sc1
	v_readlane_b32 s8, v245, 5
	v_readlane_b32 s9, v245, 6
	s_waitcnt vmcnt(0)
	v_add_u32_e32 v16, v16, v13
	s_nop 2
	global_load_dword v14, v189, s[8:9] sc1
	v_readlane_b32 s8, v245, 7
	v_readlane_b32 s9, v245, 8
	s_waitcnt vmcnt(0)
	v_add_u32_e32 v16, v16, v14
	s_nop 2
	global_load_dword v15, v189, s[8:9] sc1
	s_waitcnt vmcnt(0)
	v_add_u32_e32 v16, v16, v15
	v_cmp_eq_u32_e32 vcc, s6, v16
	s_cbranch_vccnz .LBB0_373
	s_and_b32 s1, s7, 0xff
	s_cmp_eq_u32 s1, 0
	s_mov_b64 s[36:37], -1
	s_sleep 4
	s_cbranch_scc1 .LBB0_378
	s_and_b64 vcc, exec, s[36:37]
	s_cbranch_vccz .LBB0_373

.LBB0_392:
	s_and_b32 s1, s6, 0xff
	s_mov_b64 s[64:65], -1
	s_cmp_lg_u32 s1, 0
	s_mov_b64 s[74:75], -1
	s_sleep 4
	s_cbranch_scc0 .LBB0_395
	s_and_b64 vcc, exec, s[74:75]
	s_cbranch_vccz .LBB0_391

; DI unsigned xb_ld(unsigned* p) { return __hip_atomic_load(p, __ATOMIC_RELAXED, __HIP_MEMORY_SCOPE_AGENT); }
; DI void xcd_barrier_complete(unsigned* bar, unsigned x, unsigned& nloc, unsigned& nx) {
;   const unsigned G = gridDim.x * gridDim.y * gridDim.z;
;   unsigned sum, cnt, mine, sp = 0u;
;   for (;;) {
;     sum = 0u; cnt = 0u; mine = 0u;
; #pragma unroll
;     for (unsigned j = 0; j < 16; ++j) { const unsigned c = xb_ld(&bar[XB_XCNT(j)]); sum += c; cnt += (c > 0u) ? 1u : 0u; mine = (j == x) ? c : mine; }
;     if (sum == G) break;
;     __builtin_amdgcn_s_sleep(1);
;     if ((++sp & 255u) == 0u) { if (xb_ld(&bar[XB_TMO])) break; if (sp > XB_SPIN_CAP) { atomicAdd(&bar[XB_TMO], 1u); break; } }
;   }
;   nloc = mine > 0u ? mine : 1u; nx = cnt > 0u ? cnt : 1u;
.LBB0_693:
	v_readlane_b32 s6, v246, 41
	v_readlane_b32 s7, v246, 42
	v_readlane_b32 s1, v244, 19
	s_mov_b64 s[16:17], -1
	s_mov_b64 s[26:27], -1
	s_waitcnt lgkmcnt(0)
	s_nop 0
	global_load_dword v0, v189, s[6:7] sc1
	v_readlane_b32 s6, v246, 43
	v_readlane_b32 s7, v246, 44
	s_nop 4
	global_load_dword v1, v189, s[6:7] sc1
	v_readlane_b32 s6, v246, 45
	v_readlane_b32 s7, v246, 46
	s_waitcnt vmcnt(0)
	v_add_u32_e32 v16, v1, v0
	s_nop 2
	global_load_dword v2, v189, s[6:7] sc1
	v_readlane_b32 s6, v246, 47
	v_readlane_b32 s7, v246, 48
	s_waitcnt vmcnt(0)
	v_add_u32_e32 v16, v16, v2
	s_nop 2
	global_load_dword v3, v189, s[6:7] sc1
	v_readlane_b32 s6, v246, 49
	v_readlane_b32 s7, v246, 50
	s_waitcnt vmcnt(0)
	v_add_u32_e32 v16, v16, v3
	s_nop 2
	global_load_dword v4, v189, s[6:7] sc1
	v_readlane_b32 s6, v246, 51
	v_readlane_b32 s7, v246, 52
	s_waitcnt vmcnt(0)
	v_add_u32_e32 v16, v16, v4
	s_nop 2
	global_load_dword v5, v189, s[6:7] sc1
	v_readlane_b32 s6, v246, 53
	v_readlane_b32 s7, v246, 54
	s_waitcnt vmcnt(0)
	v_add_u32_e32 v16, v16, v5
	s_nop 2
	global_load_dword v6, v189, s[6:7] sc1
	v_readlane_b32 s6, v246, 55
	v_readlane_b32 s7, v246, 56
	s_waitcnt vmcnt(0)
	v_add_u32_e32 v16, v16, v6
	s_nop 2
	global_load_dword v7, v189, s[6:7] sc1
	v_readlane_b32 s6, v246, 57
	v_readlane_b32 s7, v246, 58
	s_waitcnt vmcnt(0)
	v_add_u32_e32 v16, v16, v7
	s_nop 2
	global_load_dword v8, v189, s[6:7] sc1
	v_readlane_b32 s6, v246, 59
	v_readlane_b32 s7, v246, 60
	s_waitcnt vmcnt(0)
	v_add_u32_e32 v16, v16, v8
	s_nop 2
	global_load_dword v9, v189, s[6:7] sc1
	v_readlane_b32 s6, v246, 61
	v_readlane_b32 s7, v246, 62
	s_waitcnt vmcnt(0)
	v_add_u32_e32 v16, v16, v9
	s_nop 2
	global_load_dword v10, v189, s[6:7] sc1
	v_readlane_b32 s6, v246, 63
	v_readlane_b32 s7, v245, 0
	s_waitcnt vmcnt(0)
	v_add_u32_e32 v16, v16, v10
	s_nop 2
	global_load_dword v11, v189, s[6:7] sc1
	v_readlane_b32 s6, v245, 1
	v_readlane_b32 s7, v245, 2
	s_waitcnt vmcnt(0)
	v_add_u32_e32 v16, v16, v11
	s_nop 2
	global_load_dword v12, v189, s[6:7] sc1
	v_readlane_b32 s6, v245, 3
	v_readlane_b32 s7, v245, 4
	s_waitcnt vmcnt(0)
	v_add_u32_e32 v16, v16, v12
	s_nop 2
	global_load_dword v13, v189, s[6:7] sc1
	v_readlane_b32 s6, v245, 5
	v_readlane_b32 s7, v245, 6
	s_waitcnt vmcnt(0)
	v_add_u32_e32 v16, v16, v13
	s_nop 2
	global_load_dword v14, v189, s[6:7] sc1
	v_readlane_b32 s6, v245, 7
	v_readlane_b32 s7, v245, 8
	s_waitcnt vmcnt(0)
	v_add_u32_e32 v16, v16, v14
	s_nop 2
	global_load_dword v15, v189, s[6:7] sc1
	s_waitcnt vmcnt(0)
	v_add_u32_e32 v16, v16, v15
	v_cmp_eq_u32_e32 vcc, s1, v16
	s_cbranch_vccnz .LBB0_692
	s_and_b32 s1, s5, 0xff
	s_cmp_eq_u32 s1, 0
	s_mov_b64 s[28:29], -1
	s_sleep 4
	s_cbranch_scc1 .LBB0_697
	s_and_b64 vcc, exec, s[28:29]
	s_cbranch_vccz .LBB0_692

.LBB0_711:
	s_and_b32 s1, s5, 0xff
	s_mov_b64 s[34:35], -1
	s_cmp_lg_u32 s1, 0
	s_mov_b64 s[38:39], -1
	s_sleep 4
	s_cbranch_scc0 .LBB0_714
	s_and_b64 vcc, exec, s[38:39]
	s_cbranch_vccz .LBB0_710
